# NA bias masking: guard words before/behind the bias table initialised to -inf so masked-out reads can never carry NaN/+inf patterns (robustness of the addend-mask form); otherwise as the previous best
# baseline (speedup 1.0000x reference)
.LBB0_1064:
	s_cmp_gt_i32 s52, 10
	s_cselect_b64 s[0:1], -1, 0
	s_cmp_lt_i32 s53, 11
	s_cselect_b64 s[2:3], -1, 0
	s_or_b64 s[0:1], s[0:1], s[2:3]
	s_and_b64 vcc, exec, s[0:1]
	s_cbranch_vccnz .LBB0_1182
	s_cmpk_gt_i32 s10, 0x7ff
	s_cbranch_scc1 .LBB0_1130
	v_readlane_b32 s13, v239, 43
	s_lshr_b32 s1, s13, 7
	v_mbcnt_lo_u32_b32 v0, -1, 0
	s_and_b32 s11, s1, 0x1fffffe
	s_lshl_b32 s1, s62, 4
	v_mbcnt_hi_u32_b32 v1, -1, v0
	s_and_b32 s1, s1, 48
	v_and_b32_e32 v6, 15, v1
	v_med3_u32 v7, s1, 8, 40
	v_or_b32_e32 v2, s1, v6
	v_and_b32_e32 v4, 7, v1
	v_add_u32_e32 v10, -8, v7
	s_waitcnt lgkmcnt(1)
	v_lshrrev_b32_e32 v5, 5, v1
	v_or_b32_e32 v109, 0x100, v2
	v_med3_u32 v8, v2, 8, 56
	v_lshlrev_b32_e32 v2, 3, v4
	v_lshlrev_b32_e32 v94, 4, v4
	v_add_u16_e32 v4, v1, v10
	v_lshrrev_b16_e32 v12, 1, v4
	v_lshlrev_b32_e32 v4, 2, v5
	v_add_u32_e32 v13, v4, v7
	v_sub_u32_e32 v115, v13, v8
	v_bitop3_b32 v8, v12, v5, 7 bitop3:0x6c
	s_and_b32 s0, s13, 0xffffffc0
	v_and_b32_e32 v3, 31, v1
	v_lshlrev_b32_e32 v117, 4, v8
	v_add_u32_e32 v8, 2, v5
	v_add_u32_e32 v90, s0, v1
	v_lshlrev_b32_e32 v9, 4, v1
	s_movk_i32 s0, 0x70
	v_add_lshl_u32 v114, v3, v10, 7
	v_lshlrev_b32_e32 v116, 1, v10
	v_bitop3_b32 v10, v12, v8, 7 bitop3:0x6c
	v_bitop3_b32 v112, v90, s0, v9 bitop3:0x48
	v_lshrrev_b32_e32 v9, 1, v1
	v_lshlrev_b32_e32 v118, 4, v10
	v_or_b32_e32 v10, 4, v5
	s_waitcnt lgkmcnt(0)
	v_bfe_u32 v11, v1, 1, 3
	v_bitop3_b32 v10, v12, v10, 7 bitop3:0x6c
	v_bitop3_b32 v8, v8, v9, 7 bitop3:0x78
	v_lshlrev_b32_e32 v119, 4, v10
	v_add_u32_e32 v10, 6, v5
	v_lshlrev_b32_e32 v122, 4, v8
	v_bitop3_b32 v8, v5, v11, 4 bitop3:0x36
	v_lshlrev_b32_e32 v123, 4, v8
	v_bitop3_b32 v8, v10, v9, 7 bitop3:0x78
	v_lshlrev_b32_e32 v124, 4, v8
	v_max_i32_e32 v8, 0xffffffd1, v90
	v_sub_u32_e32 v8, v8, v90
	v_bitop3_b32 v12, v12, v10, 7 bitop3:0x6c
	v_add_u32_e32 v8, 0x1ff, v8
	v_lshlrev_b32_e32 v120, 4, v12
	v_bitop3_b32 v12, v9, v5, 7 bitop3:0x6c
	v_lshrrev_b32_e32 v9, 9, v8
	v_bfe_u32 v108, v1, 4, 1
	v_add_u32_e32 v10, 1, v9
	v_add_u32_e32 v9, -1, v9
	v_lshlrev_b32_e32 v1, 2, v1
	v_lshrrev_b32_e32 v11, 1, v9
	v_lshl_add_u32 v1, s62, 8, v1
	v_add_u32_e32 v126, 0x21100, v1
	v_add_u16_e32 v1, 1, v11
	v_lshlrev_b32_e32 v0, 3, v5
	s_movk_i32 s12, 0x88
	v_and_b32_e32 v128, 7, v1
	v_lshlrev_b32_e32 v1, 2, v7
	v_ashrrev_i32_e32 v92, 3, v90
	v_lshlrev_b32_e32 v113, 7, v3
	v_mad_u32_u24 v125, v3, s12, v0
	v_lshl_add_u32 v1, v5, 4, v1
	v_lshlrev_b32_e32 v3, 2, v6
	v_mul_lo_u32 v110, v92, s12
	v_sub_u32_e32 v1, v1, v3
	s_and_b32 s12, s13, 0xc0
	v_subrev_u32_e32 v1, s12, v1
	v_mul_u32_u24_e32 v3, 0x7c, v108
	s_lshr_b32 s12, s13, 8
	v_mov_b32_e32 v89, 0
	v_lshlrev_b32_e32 v121, 4, v12
	v_readlane_b32 s36, v239, 32
	s_movk_i32 s2, 0x1ff
	v_add_u32_e32 v12, 1, v11
	v_sub_u32_e32 v1, v1, v3
	s_mulk_i32 s12, 0xf8
	s_movk_i32 s0, 0x1d1
	v_mov_b32_e32 v95, v89
	v_readlane_b32 s37, v239, 33
	v_readlane_b32 s42, v239, 38
	v_readlane_b32 s43, v239, 39
	v_cmp_lt_u32_e64 s[2:3], s2, v8
	v_and_b32_e32 v8, 0xfffffe, v10
	v_and_b32_e32 v13, 7, v12
	v_subrev_u32_e32 v1, s12, v1
	s_mov_b32 s23, 0
	v_ashrrev_i32_e32 v93, 31, v92
	v_lshlrev_b32_e32 v111, 7, v92
	v_cmp_gt_i32_e64 s[0:1], s0, v90
	v_lshl_add_u64 v[96:97], s[42:43], 0, v[94:95]
	v_lshl_add_u32 v95, v8, 9, v90
	v_add_u32_e32 v91, 0x200, v90
	v_cmp_lt_u32_e64 s[4:5], 13, v9
	v_cmp_ne_u32_e64 s[6:7], 0, v13
	v_cmp_ne_u32_e64 s[8:9], v10, v8
	v_and_b32_e32 v127, -8, v12
	v_add_u32_e32 v129, 0x21290, v1
	v_mov_b32_e32 v130, 0x900
	v_lshlrev_b32_e32 v98, 1, v0
	v_mov_b32_e32 v99, v89
	v_lshlrev_b32_e32 v100, 1, v2
	v_mov_b32_e32 v101, v89
	s_movk_i32 s33, 0x1200
	s_movk_i32 s34, 0x2000
	s_mov_b64 s[24:25], 0x800
	s_movk_i32 s35, 0xffd0
	s_movk_i32 s36, 0xffef
	s_mov_b32 s37, 0xff800000
	v_lshlrev_b32_e32 v88, 1, v4
	v_mov_b32_e32 v131, 0x21900
	v_mov_b32_e32 v132, 0x21100
	v_mov_b32_e32 v133, 0x3e8
	s_mov_b32 s44, s10
	s_mov_b32 s45, s10
	v_readlane_b32 s38, v239, 34
	v_readlane_b32 s39, v239, 35
	v_readlane_b32 s40, v239, 36
	v_readlane_b32 s41, v239, 37
	v_mov_b32_e32 v214, 0xff800000
	v_mov_b32_e32 v215, 0
	v_cmp_gt_u32_e32 vcc, 16, v115
	v_cndmask_b32_e32 v196, v214, v215, vcc
	v_add_u32_e32 v213, 1, v115
	v_cmp_gt_u32_e32 vcc, 16, v213
	v_cndmask_b32_e32 v197, v214, v215, vcc
	v_add_u32_e32 v213, 2, v115
	v_cmp_gt_u32_e32 vcc, 16, v213
	v_cndmask_b32_e32 v198, v214, v215, vcc
	v_add_u32_e32 v213, 3, v115
	v_cmp_gt_u32_e32 vcc, 16, v213
	v_cndmask_b32_e32 v199, v214, v215, vcc
	v_add_u32_e32 v213, 8, v115
	v_cmp_gt_u32_e32 vcc, 16, v213
	v_cndmask_b32_e32 v200, v214, v215, vcc
	v_add_u32_e32 v213, 9, v115
	v_cmp_gt_u32_e32 vcc, 16, v213
	v_cndmask_b32_e32 v201, v214, v215, vcc
	v_add_u32_e32 v213, 10, v115
	v_cmp_gt_u32_e32 vcc, 16, v213
	v_cndmask_b32_e32 v202, v214, v215, vcc
	v_add_u32_e32 v213, 11, v115
	v_cmp_gt_u32_e32 vcc, 16, v213
	v_cndmask_b32_e32 v203, v214, v215, vcc
	v_add_u32_e32 v213, 16, v115
	v_cmp_gt_u32_e32 vcc, 16, v213
	v_cndmask_b32_e32 v204, v214, v215, vcc
	v_add_u32_e32 v213, 17, v115
	v_cmp_gt_u32_e32 vcc, 16, v213
	v_cndmask_b32_e32 v205, v214, v215, vcc
	v_add_u32_e32 v213, 18, v115
	v_cmp_gt_u32_e32 vcc, 16, v213
	v_cndmask_b32_e32 v206, v214, v215, vcc
	v_add_u32_e32 v213, 19, v115
	v_cmp_gt_u32_e32 vcc, 16, v213
	v_cndmask_b32_e32 v207, v214, v215, vcc
	v_add_u32_e32 v213, 24, v115
	v_cmp_gt_u32_e32 vcc, 16, v213
	v_cndmask_b32_e32 v208, v214, v215, vcc
	v_add_u32_e32 v213, 25, v115
	v_cmp_gt_u32_e32 vcc, 16, v213
	v_cndmask_b32_e32 v209, v214, v215, vcc
	v_add_u32_e32 v213, 26, v115
	v_cmp_gt_u32_e32 vcc, 16, v213
	v_cndmask_b32_e32 v210, v214, v215, vcc
	v_add_u32_e32 v213, 27, v115
	v_cmp_gt_u32_e32 vcc, 16, v213
	v_cndmask_b32_e32 v211, v214, v215, vcc
	v_mbcnt_lo_u32_b32 v213, -1, 0
	v_mbcnt_hi_u32_b32 v213, -1, v213
	v_and_b32_e32 v216, 15, v213
	v_lshlrev_b32_e32 v216, 2, v216
	v_mov_b32_e32 v212, 0x21880
	v_lshl_add_u32 v213, v213, 2, v212
	ds_write_b32 v213, v214
	v_add_u32_e32 v213, 0x210c0, v216
	ds_write_b32 v213, v214
	v_add_u32_e32 v213, 0x21844, v216
	ds_write_b32 v213, v214
	s_branch .LBB0_1069
